# P0 row pass: 64-lane sum of squares by DPP row shifts/broadcasts instead of six dependent ds_bpermute round trips
# speedup vs baseline: 1.0024x; 1.0024x over previous
; #define GAS __attribute__((address_space(1)))
; __device__ __forceinline__ unsigned pk2(float lo, float hi) { return pg8::cvt_pk_bf16(lo, hi); }
; __device__ __forceinline__ float wave_sum(float v) {
; #pragma unroll
;     for (int o = 1; o < 64; o <<= 1) v += __shfl_xor(v, o);
;     return v;
; }
; __global__ void __launch_bounds__(NWAVES * 64, 2) mk_fwd(Args args) {
;     ...
;         for (int m = gw; m < T; m += NGW) {
;             const GAS f32x4* xr = (const GAS f32x4*)(x + (size_t)m * DM) + lane; f32x4 v[8]; float s = 0.f;
; #pragma unroll
;             for (int j = 0; j < 8; ++j) { v[j] = __builtin_nontemporal_load(&xr[64 * j]); s += (v[j].x * v[j].x + v[j].y * v[j].y) + (v[j].z * v[j].z + v[j].w * v[j].w); }
;             s = wave_sum(s);
;             if (lane == 0) { const float iv = 1.0f / sqrtf(s * (1.0f / DM) + EPS); inv0[m] = iv; }
;             GAS unsigned long long* o8 = (GAS unsigned long long*)(xb + (size_t)m * DM) + lane;
; #pragma unroll
;             for (int j = 0; j < 8; ++j) o8[64 * j] = (unsigned long long)pk2(v[j].x, v[j].y) | ((unsigned long long)pk2(v[j].z, v[j].w) << 32);
;         }
.LBB0_14:
	v_add_co_u32_e32 v48, vcc, 0xfffff000, v38
	global_load_dwordx4 v[2:5], v[38:39], off offset:-3072 nt
	global_load_dwordx4 v[6:9], v[38:39], off offset:-2048 nt
	global_load_dwordx4 v[10:13], v[38:39], off offset:-1024 nt
	global_load_dwordx4 v[14:17], v[38:39], off nt
	v_addc_co_u32_e32 v49, vcc, -1, v39, vcc
	global_load_dwordx4 v[30:33], v[48:49], off offset:-3072 nt
	global_load_dwordx4 v[26:29], v[48:49], off offset:-2048 nt
	global_load_dwordx4 v[22:25], v[48:49], off offset:-1024 nt
	global_load_dwordx4 v[18:21], v[38:39], off offset:-4096 nt
	s_waitcnt vmcnt(7)
	v_mul_f32_e32 v47, v3, v3
	v_mul_f32_e32 v48, v5, v5
	s_waitcnt vmcnt(6)
	v_mul_f32_e32 v49, v7, v7
	v_mul_f32_e32 v50, v9, v9
	s_waitcnt vmcnt(5)
	v_mul_f32_e32 v51, v11, v11
	v_mul_f32_e32 v52, v13, v13
	s_waitcnt vmcnt(3)
	v_mul_f32_e32 v55, v31, v31
	v_mul_f32_e32 v56, v33, v33
	s_waitcnt vmcnt(2)
	v_mul_f32_e32 v57, v27, v27
	v_mul_f32_e32 v58, v29, v29
	v_fmac_f32_e32 v47, v2, v2
	v_fmac_f32_e32 v48, v4, v4
	v_fmac_f32_e32 v49, v6, v6
	v_fmac_f32_e32 v50, v8, v8
	v_fmac_f32_e32 v51, v10, v10
	v_fmac_f32_e32 v52, v12, v12
	s_waitcnt vmcnt(1)
	v_mul_f32_e32 v59, v23, v23
	v_mul_f32_e32 v60, v25, v25
	v_fmac_f32_e32 v55, v30, v30
	v_fmac_f32_e32 v56, v32, v32
	v_fmac_f32_e32 v57, v26, v26
	v_fmac_f32_e32 v58, v28, v28
	s_waitcnt vmcnt(0)
	v_mul_f32_e32 v61, v19, v19
	v_mul_f32_e32 v62, v21, v21
	v_add_f32_e32 v47, v47, v48
	v_add_f32_e32 v48, v49, v50
	v_add_f32_e32 v49, v51, v52
	v_fmac_f32_e32 v59, v22, v22
	v_fmac_f32_e32 v60, v24, v24
	v_add_f32_e32 v50, v55, v56
	v_add_f32_e32 v51, v57, v58
	v_fmac_f32_e32 v61, v18, v18
	v_fmac_f32_e32 v62, v20, v20
	v_add_f32_e32 v52, v59, v60
	v_add_f32_e32 v50, v50, v51
	v_add_f32_e32 v55, v61, v62
	v_add_f32_e32 v50, v50, v52
	v_add_f32_e32 v50, v50, v55
	v_mul_f32_e32 v53, v15, v15
	v_mul_f32_e32 v54, v17, v17
	v_add_f32_e32 v47, v50, v47
	v_fmac_f32_e32 v53, v14, v14
	v_fmac_f32_e32 v54, v16, v16
	v_add_f32_e32 v47, v47, v48
	v_add_f32_e32 v47, v47, v49
	v_add_f32_e32 v48, v53, v54
	v_add_f32_e32 v47, v47, v48
	s_nop 1
	v_add_f32_dpp v47, v47, v47 row_shr:1 row_mask:0xf bank_mask:0xf bound_ctrl:1
	s_nop 1
	v_add_f32_dpp v47, v47, v47 row_shr:2 row_mask:0xf bank_mask:0xf bound_ctrl:1
	s_nop 1
	v_add_f32_dpp v47, v47, v47 row_shr:4 row_mask:0xf bank_mask:0xf bound_ctrl:1
	s_nop 1
	v_add_f32_dpp v47, v47, v47 row_shr:8 row_mask:0xf bank_mask:0xf bound_ctrl:1
	s_nop 1
	v_add_f32_dpp v47, v47, v47 row_bcast:15 row_mask:0xa bank_mask:0xf
	s_nop 1
	v_add_f32_dpp v47, v47, v47 row_bcast:31 row_mask:0xc bank_mask:0xf
	s_nop 1
	v_readlane_b32 s4, v47, 63
	s_and_saveexec_b64 s[26:27], s[0:1]
	s_cbranch_execz .LBB0_13
	v_mov_b32_e32 v47, s4
	v_fmamk_f32 v47, v47, 0x3a000000, v36
	v_mul_f32_e32 v48, 0x4f800000, v47
	v_cmp_gt_f32_e32 vcc, s30, v47
	s_nop 1
	v_cndmask_b32_e32 v47, v47, v48, vcc
	v_sqrt_f32_e32 v48, v47
	s_nop 0
	v_add_u32_e32 v49, -1, v48
	v_fma_f32 v51, -v49, v48, v47
	v_add_u32_e32 v50, 1, v48
	v_cmp_ge_f32_e64 s[4:5], 0, v51
	s_nop 1
	v_cndmask_b32_e64 v49, v48, v49, s[4:5]
	v_fma_f32 v48, -v50, v48, v47
	v_cmp_lt_f32_e64 s[4:5], 0, v48
	s_nop 1
	v_cndmask_b32_e64 v48, v49, v50, s[4:5]
	v_mul_f32_e32 v49, 0x37800000, v48
	v_cndmask_b32_e32 v48, v48, v49, vcc
	v_cmp_class_f32_e32 vcc, v47, v46
	s_nop 1
	v_cndmask_b32_e32 v47, v48, v47, vcc
	v_div_scale_f32 v48, s[4:5], v47, v47, 1.0
	v_rcp_f32_e32 v49, v48
	s_add_u32 s4, s94, s28
	s_addc_u32 s5, s95, s29
	v_fma_f32 v50, -v48, v49, 1.0
	v_fmac_f32_e32 v49, v50, v49
	v_div_scale_f32 v50, vcc, 1.0, v47, 1.0
	v_mul_f32_e32 v51, v50, v49
	v_fma_f32 v52, -v48, v51, v50
	v_fmac_f32_e32 v51, v52, v49
	v_fma_f32 v48, -v48, v51, v50
	v_div_fmas_f32 v48, v48, v49, v51
	v_div_fixup_f32 v47, v48, v47, 1.0
	global_store_dword v37, v47, s[4:5]
	s_branch .LBB0_13
